# mixer-A pass 2: dilation-1 key tiles swept first by a block-synchronous loop that stages each K/V tile once per workgroup in LDS (quarter per wave, 3 rotating buffers); per-wave loop keeps the dilatio
# speedup vs baseline: 1.1741x; 1.0054x over previous
.LBB0_705:
	s_add_i32 s39, s40, 0x180
	s_lshr_b32 s43, s42, 2
	s_lshl_b32 s40, s44, 5
	s_add_i32 s40, s43, s40
	s_add_i32 s45, s40, 0xffffff80
	v_lshlrev_b32_e32 v36, 3, v34
	v_lshlrev_b32_e32 v30, 16, v0
	v_and_b32_e32 v31, 0xffff0000, v0
	v_or_b32_e32 v0, s45, v159
	v_or_b32_e32 v36, s39, v36
	s_ashr_i32 s39, s38, 31
	s_ashr_i32 s40, s45, 5
	v_lshl_add_u32 v38, v0, 2, v158
	s_ashr_i32 s41, s40, 31
	s_lshl_b64 s[38:39], s[38:39], 19
	v_ashrrev_i32_e32 v39, 31, v38
	s_lshl_b64 s[40:41], s[40:41], 12
	v_lshl_add_u64 v[170:171], v[160:161], 0, s[38:39]
	v_lshl_add_u64 v[38:39], s[0:1], 0, v[38:39]
	v_mov_b64_e32 v[42:43], s[66:67]
	v_lshl_add_u64 v[40:41], v[170:171], 0, s[40:41]
	v_mad_u64_u32 v[42:43], s[40:41], v38, s80, v[42:43]
	v_mov_b32_e32 v37, v1
	v_and_b32_e32 v35, 63, v2
	v_mad_i32_i24 v43, v39, s80, v43
	v_lshlrev_b64 v[36:37], 1, v[36:37]
	v_lshlrev_b32_e32 v0, 5, v35
	v_lshl_add_u64 v[38:39], v[42:43], 0, v[36:37]
	v_lshl_add_u64 v[40:41], v[40:41], 0, v[0:1]
	v_and_b32_e32 v238, 63, v199
	v_lshrrev_b32_e32 v239, 3, v238
	v_and_b32_e32 v240, 31, v238
	v_sub_u32_e32 v224, v239, v240
	v_add_u32_e32 v225, 8, v224
	v_add_u32_e32 v226, 16, v224
	v_add_u32_e32 v227, 24, v224
	v_lshrrev_b32_e32 v241, 5, v238
	v_and_b32_e32 v242, 7, v238
	v_lshrrev_b32_e32 v243, 4, v238
	v_xor_b32_e32 v228, v242, v243
	v_xor_b32_e32 v229, 4, v228
	v_sub_u32_e32 v228, v228, v241
	v_sub_u32_e32 v229, v229, v241
	v_lshlrev_b32_e32 v228, 4, v228
	v_lshlrev_b32_e32 v229, 4, v229
	v_lshrrev_b32_e32 v250, 6, v199
	v_lshlrev_b32_e32 v250, 13, v250
	v_bfe_u32 v251, v238, 1, 3
	v_xor_b32_e32 v251, v251, v241
	v_lshlrev_b32_e32 v251, 4, v251
	v_lshl_add_u32 v251, v240, 7, v251
	v_add_u32_e32 v234, v250, v251
	v_xor_b32_e32 v235, 0x20, v234
	v_xor_b32_e32 v236, 0x40, v234
	v_xor_b32_e32 v237, 0x60, v234
	v_readfirstlane_b32 s98, v250
	s_mov_b32 s99, 0x7000
	s_add_u32 m0, s98, 0x0
	v_mad_i64_i32 v[232:233], s[100:101], v224, s99, v[38:39]
	v_add_u32_e32 v232, v228, v232
	global_load_lds_dwordx4 v[232:233], off
	s_add_u32 m0, s98, 0x400
	v_mad_i64_i32 v[232:233], s[100:101], v225, s99, v[38:39]
	v_add_u32_e32 v232, v229, v232
	global_load_lds_dwordx4 v[232:233], off
	s_add_u32 m0, s98, 0x800
	v_mad_i64_i32 v[232:233], s[100:101], v226, s99, v[38:39]
	v_add_u32_e32 v232, v228, v232
	global_load_lds_dwordx4 v[232:233], off
	s_add_u32 m0, s98, 0xc00
	v_mad_i64_i32 v[232:233], s[100:101], v227, s99, v[38:39]
	v_add_u32_e32 v232, v229, v232
	global_load_lds_dwordx4 v[232:233], off
	v_and_b32_e32 v230, 63, v199
	v_lshlrev_b32_e32 v230, 4, v230
	v_sub_u32_e32 v230, 0, v230
	v_ashrrev_i32_e32 v231, 31, v230
	v_lshl_add_u64 v[230:231], v[40:41], 0, v[230:231]
	global_load_dwordx4 v[110:113], v[230:231], off
	global_load_dwordx4 v[106:109], v[230:231], off offset:1024
	global_load_dwordx4 v[102:105], v[230:231], off offset:2048
	global_load_dwordx4 v[98:101], v[230:231], off offset:3072
	v_readlane_b32 s12, v253, 2
	v_lshlrev_b32_e32 v167, 2, v34
	v_readlane_b32 s13, v253, 3
	v_readlane_b32 s23, v253, 13
	v_readlane_b32 s24, v253, 14
	v_readlane_b32 s25, v253, 15
	v_readlane_b32 s26, v253, 16
	v_readlane_b32 s27, v253, 17
	s_add_u32 s45, s12, s38
	v_lshlrev_b32_e32 v2, 16, v4
	v_and_b32_e32 v3, 0xffff0000, v4
	v_lshlrev_b32_e32 v4, 16, v5
	v_and_b32_e32 v5, 0xffff0000, v5
	v_lshlrev_b32_e32 v6, 16, v8
	v_and_b32_e32 v7, 0xffff0000, v8
	v_lshlrev_b32_e32 v8, 16, v9
	v_and_b32_e32 v9, 0xffff0000, v9
	v_lshlrev_b32_e32 v10, 16, v12
	v_and_b32_e32 v11, 0xffff0000, v12
	v_lshlrev_b32_e32 v12, 16, v13
	v_and_b32_e32 v13, 0xffff0000, v13
	v_lshlrev_b32_e32 v14, 16, v16
	v_and_b32_e32 v15, 0xffff0000, v16
	v_lshlrev_b32_e32 v16, 16, v17
	v_and_b32_e32 v17, 0xffff0000, v17
	v_lshlrev_b32_e32 v18, 16, v20
	v_and_b32_e32 v19, 0xffff0000, v20
	v_lshlrev_b32_e32 v20, 16, v21
	v_and_b32_e32 v21, 0xffff0000, v21
	v_lshlrev_b32_e32 v22, 16, v24
	v_and_b32_e32 v23, 0xffff0000, v24
	v_lshlrev_b32_e32 v24, 16, v25
	v_and_b32_e32 v25, 0xffff0000, v25
	v_lshlrev_b32_e32 v26, 16, v28
	v_and_b32_e32 v27, 0xffff0000, v28
	v_lshlrev_b32_e32 v28, 16, v29
	v_and_b32_e32 v29, 0xffff0000, v29
	v_lshlrev_b32_e32 v32, 16, v33
	v_and_b32_e32 v33, 0xffff0000, v33
	v_lshlrev_b32_e32 v172, 4, v35
	v_or_b32_e32 v173, 0x80, v167
	v_lshl_add_u64 v[174:175], s[66:67], 0, v[36:37]
	v_or_b32_e32 v178, s43, v159
	s_addc_u32 s46, s13, s39
	s_mov_b32 s23, 0x800000
	s_movk_i32 s24, 0xf00
	s_movk_i32 s25, 0x104
	s_mov_b64 s[26:27], 0x400c0
	v_readlane_b32 s14, v253, 4
	v_readlane_b32 s15, v253, 5
	v_readlane_b32 s16, v253, 6
	v_readlane_b32 s17, v253, 7
	v_readlane_b32 s18, v253, 8
	v_readlane_b32 s19, v253, 9
	v_readlane_b32 s20, v253, 10
	v_readlane_b32 s21, v253, 11
	v_readlane_b32 s22, v253, 12
	v_writelane_b32 v156, s38, 0
	v_writelane_b32 v156, s39, 1
	v_writelane_b32 v156, s40, 2
	v_writelane_b32 v156, s41, 3
	v_writelane_b32 v156, s42, 4
	v_writelane_b32 v156, s43, 5
	v_writelane_b32 v156, s44, 6
	v_writelane_b32 v156, s45, 7
	v_writelane_b32 v156, s46, 8
	v_writelane_b32 v156, s47, 9
	v_writelane_b32 v156, s48, 10
	v_writelane_b32 v156, s49, 11
	s_ashr_i32 s47, s30, 2
	s_and_b32 s47, s47, -8
	v_readlane_b32 s48, v254, 38
	s_add_i32 s47, s47, s48
	s_mul_hi_i32 s48, s47, 0x2aaaaaab
	s_lshr_b32 s49, s48, 31
	s_add_i32 s48, s48, s49
	s_mul_i32 s49, s48, 6
	s_sub_i32 s49, s47, s49
	s_cmp_eq_u32 s42, 0
	s_cselect_b32 s100, 4, 0
	s_lshl_b32 s101, s100, 5
	s_add_i32 s101, s101, s42
	s_add_i32 s101, s101, 0xffffff80
	s_lshl_b32 s40, s101, 7
	s_add_u32 s40, s45, s40
	s_addc_u32 s41, s46, 0
	s_lshl_b32 s48, s48, 12
	s_add_i32 s48, s48, s101
	s_mul_i32 s38, s48, 0x1c00
	s_mul_hi_u32 s39, s48, 0x1c00
	s_lshl_b32 s49, s49, 7
	s_add_i32 s49, s49, 0x300
	s_add_u32 s38, s38, s49
	s_addc_u32 s39, s39, 0
	s_add_u32 s38, s38, s66
	s_addc_u32 s39, s39, s67
	s_mov_b32 s42, s100
	v_and_b32_e32 v146, 63, v199
	v_lshrrev_b32_e32 v147, 6, v199
	v_lshrrev_b32_e32 v148, 3, v146
	v_lshl_add_u32 v148, v147, 3, v148
	v_mul_u32_u24_e32 v58, 0x1c00, v148
	v_bfe_u32 v148, v148, 1, 3
	v_and_b32_e32 v155, 7, v146
	v_xor_b32_e32 v148, v148, v155
	v_lshl_add_u32 v58, v148, 4, v58
	v_lshlrev_b32_e32 v59, 4, v199
	v_lshlrev_b32_e32 v64, 4, v146
	v_and_b32_e32 v155, 31, v146
	v_lshrrev_b32_e32 v154, 5, v146
	v_bfe_u32 v148, v155, 1, 3
	v_xor_b32_e32 v148, v148, v154
	v_lshlrev_b32_e32 v148, 4, v148
	v_lshl_add_u32 v60, v155, 7, v148
	v_xor_b32_e32 v61, 0x20, v60
	v_xor_b32_e32 v62, 0x40, v60
	v_xor_b32_e32 v63, 0x60, v60
	v_lshl_add_u32 v65, v155, 2, v147
	v_add_u32_e32 v65, 0x80, v65
	s_lshl_b32 s47, s42, 5
	v_subrev_u32_e32 v65, s47, v65
	v_lshlrev_b32_e32 v155, 2, v154
	v_mov_b32_e32 v150, 0xf149f2ca
	v_mov_b32_e32 v151, 0x80
	v_mov_b32_e32 v153, 0
	v_add_u32_e32 v34, 0, v155
	v_add_u32_e32 v35, 1, v155
	v_add_u32_e32 v36, 2, v155
	v_add_u32_e32 v37, 3, v155
	v_add_u32_e32 v38, 8, v155
	v_add_u32_e32 v39, 9, v155
	v_add_u32_e32 v40, 10, v155
	v_add_u32_e32 v41, 11, v155
	v_add_u32_e32 v42, 16, v155
	v_add_u32_e32 v43, 17, v155
	v_add_u32_e32 v44, 18, v155
	v_add_u32_e32 v45, 19, v155
	v_add_u32_e32 v46, 24, v155
	v_add_u32_e32 v47, 25, v155
	v_add_u32_e32 v48, 26, v155
	v_add_u32_e32 v49, 27, v155
	v_lshlrev_b32_e32 v147, 10, v147
	s_nop 0
	v_readfirstlane_b32 s46, v147
	s_add_u32 s46, s46, 0x8000
	s_mov_b32 s43, 0
	s_movk_i32 s44, 0x2000
	s_movk_i32 s45, 0x4000
	s_barrier
	s_add_u32 s47, s46, s43
	s_mov_b32 m0, s47
	s_nop 0
	global_load_lds_dwordx4 v58, s[38:39]
	s_add_u32 m0, s47, 0x1000
	s_nop 0
	global_load_lds_dwordx4 v59, s[40:41]
	s_add_u32 s100, s42, 1
	s_cmp_lt_u32 s100, 8
	s_cselect_b32 s48, 0x38000, 0
	s_cselect_b32 s49, 0x1000, 0
	s_add_u32 s38, s38, s48
	s_addc_u32 s39, s39, 0
	s_add_u32 s40, s40, s49
	s_addc_u32 s41, s41, 0
	s_add_u32 s47, s46, s44
	s_mov_b32 m0, s47
	s_nop 0
	global_load_lds_dwordx4 v58, s[38:39]
	s_add_u32 m0, s47, 0x1000
	s_nop 0
	global_load_lds_dwordx4 v59, s[40:41]
	s_add_u32 s100, s42, 2
	s_cmp_lt_u32 s100, 8
	s_cselect_b32 s48, 0x38000, 0
	s_cselect_b32 s49, 0x1000, 0
	s_add_u32 s38, s38, s48
	s_addc_u32 s39, s39, 0
	s_add_u32 s40, s40, s49
	s_addc_u32 s41, s41, 0
.Lmx_loop:
	s_waitcnt vmcnt(2)
	s_barrier
	s_add_u32 s47, s46, s45
	s_mov_b32 m0, s47
	s_nop 0
	global_load_lds_dwordx4 v58, s[38:39]
	s_add_u32 m0, s47, 0x1000
	s_nop 0
	global_load_lds_dwordx4 v59, s[40:41]
	s_add_u32 s100, s42, 3
	s_cmp_lt_u32 s100, 8
	s_cselect_b32 s48, 0x38000, 0
	s_cselect_b32 s49, 0x1000, 0
	s_add_u32 s38, s38, s48
	s_addc_u32 s39, s39, 0
	s_add_u32 s40, s40, s49
	s_addc_u32 s41, s41, 0
	v_add_u32_e32 v146, s43, v60
	v_add_u32_e32 v147, s43, v61
	ds_read_b128 v[114:117], v146 offset:32768
	ds_read_b128 v[118:121], v147 offset:32768
	v_add_u32_e32 v148, s43, v62
	v_add_u32_e32 v155, s43, v63
	ds_read_b128 v[122:125], v148 offset:32768
	ds_read_b128 v[126:129], v155 offset:32768
	v_add_u32_e32 v146, s43, v64
	ds_read_b128 v[130:133], v146 offset:36864
	ds_read_b128 v[134:137], v146 offset:37888
	ds_read_b128 v[138:141], v146 offset:38912
	ds_read_b128 v[142:145], v146 offset:39936
	v_subrev_u32_e32 v149, 0x80, v65
	s_waitcnt lgkmcnt(7)
	v_mfma_f32_32x32x16_bf16 v[66:81], v[114:117], v[82:85], 0
	s_waitcnt lgkmcnt(6)
	v_mfma_f32_32x32x16_bf16 v[66:81], v[118:121], v[86:89], v[66:81]
	s_waitcnt lgkmcnt(5)
	v_mfma_f32_32x32x16_bf16 v[66:81], v[122:125], v[90:93], v[66:81]
	s_waitcnt lgkmcnt(4)
	v_mfma_f32_32x32x16_bf16 v[66:81], v[126:129], v[94:97], v[66:81]
	s_nop 15
	s_nop 3
	v_sub_u32_e32 v146, v34, v149
	v_sub_u32_e32 v147, v35, v149
	v_sub_u32_e32 v148, v36, v149
	v_cmp_ge_u32_e64 s[48:49], v151, v146
	v_cmp_ge_u32_e64 s[100:101], v151, v147
	v_cmp_ge_u32_e64 vcc, v151, v148
	v_cndmask_b32_e64 v66, v150, v66, s[48:49]
	v_cndmask_b32_e64 v67, v150, v67, s[100:101]
	v_cndmask_b32_e64 v68, v150, v68, vcc
	v_sub_u32_e32 v146, v37, v149
	v_sub_u32_e32 v147, v38, v149
	v_sub_u32_e32 v148, v39, v149
	v_cmp_ge_u32_e64 s[48:49], v151, v146
	v_cmp_ge_u32_e64 s[100:101], v151, v147
	v_cmp_ge_u32_e64 vcc, v151, v148
	v_cndmask_b32_e64 v69, v150, v69, s[48:49]
	v_cndmask_b32_e64 v70, v150, v70, s[100:101]
	v_cndmask_b32_e64 v71, v150, v71, vcc
	v_sub_u32_e32 v146, v40, v149
	v_sub_u32_e32 v147, v41, v149
	v_sub_u32_e32 v148, v42, v149
	v_cmp_ge_u32_e64 s[48:49], v151, v146
	v_cmp_ge_u32_e64 s[100:101], v151, v147
	v_cmp_ge_u32_e64 vcc, v151, v148
	v_cndmask_b32_e64 v72, v150, v72, s[48:49]
	v_cndmask_b32_e64 v73, v150, v73, s[100:101]
	v_cndmask_b32_e64 v74, v150, v74, vcc
	v_sub_u32_e32 v146, v43, v149
	v_sub_u32_e32 v147, v44, v149
	v_sub_u32_e32 v148, v45, v149
	v_cmp_ge_u32_e64 s[48:49], v151, v146
	v_cmp_ge_u32_e64 s[100:101], v151, v147
	v_cmp_ge_u32_e64 vcc, v151, v148
	v_cndmask_b32_e64 v75, v150, v75, s[48:49]
	v_cndmask_b32_e64 v76, v150, v76, s[100:101]
	v_cndmask_b32_e64 v77, v150, v77, vcc
	v_sub_u32_e32 v146, v46, v149
	v_sub_u32_e32 v147, v47, v149
	v_sub_u32_e32 v148, v48, v149
	v_cmp_ge_u32_e64 s[48:49], v151, v146
	v_cmp_ge_u32_e64 s[100:101], v151, v147
	v_cmp_ge_u32_e64 vcc, v151, v148
	v_cndmask_b32_e64 v78, v150, v78, s[48:49]
	v_cndmask_b32_e64 v79, v150, v79, s[100:101]
	v_cndmask_b32_e64 v80, v150, v80, vcc
	v_sub_u32_e32 v146, v49, v149
	v_cmp_ge_u32_e64 s[48:49], v151, v146
	s_nop 1
	v_cndmask_b32_e64 v81, v150, v81, s[48:49]
	v_max3_f32 v146, v66, v67, v68
	v_max3_f32 v147, v69, v70, v71
	v_max3_f32 v148, v72, v73, v74
	v_max3_f32 v155, v75, v76, v77
	v_max3_f32 v154, v78, v79, v80
	v_max3_f32 v146, v146, v147, v81
	v_max3_f32 v154, v148, v155, v154
	v_max_f32_e32 v154, v146, v154
	v_mov_b32_e32 v155, v154
	s_nop 1
	v_permlane32_swap_b32_e32 v154, v155
	v_max_f32_e32 v154, v154, v155
	v_add_f32_e32 v155, 0x41800000, v168
	v_cmp_gt_f32_e32 vcc, v154, v155
	s_cbranch_vccz .Lmx_norescale
	s_nop 0
	v_cndmask_b32_e32 v155, v168, v154, vcc
	v_sub_f32_e32 v152, v168, v155
	v_exp_f32_e32 v152, v152
	v_mov_b32_e32 v168, v155
	s_nop 0
	v_mul_f32_e32 v169, v169, v152
	v_pk_mul_f32 v[2:3], v[2:3], v[152:153] op_sel_hi:[1,0]
	v_pk_mul_f32 v[4:5], v[4:5], v[152:153] op_sel_hi:[1,0]
	v_pk_mul_f32 v[6:7], v[6:7], v[152:153] op_sel_hi:[1,0]
	v_pk_mul_f32 v[8:9], v[8:9], v[152:153] op_sel_hi:[1,0]
	v_pk_mul_f32 v[10:11], v[10:11], v[152:153] op_sel_hi:[1,0]
	v_pk_mul_f32 v[12:13], v[12:13], v[152:153] op_sel_hi:[1,0]
	v_pk_mul_f32 v[14:15], v[14:15], v[152:153] op_sel_hi:[1,0]
	v_pk_mul_f32 v[16:17], v[16:17], v[152:153] op_sel_hi:[1,0]
	v_pk_mul_f32 v[18:19], v[18:19], v[152:153] op_sel_hi:[1,0]
	v_pk_mul_f32 v[20:21], v[20:21], v[152:153] op_sel_hi:[1,0]
	v_pk_mul_f32 v[22:23], v[22:23], v[152:153] op_sel_hi:[1,0]
	v_pk_mul_f32 v[24:25], v[24:25], v[152:153] op_sel_hi:[1,0]
	v_pk_mul_f32 v[26:27], v[26:27], v[152:153] op_sel_hi:[1,0]
	v_pk_mul_f32 v[28:29], v[28:29], v[152:153] op_sel_hi:[1,0]
	v_pk_mul_f32 v[30:31], v[30:31], v[152:153] op_sel_hi:[1,0]
	v_pk_mul_f32 v[32:33], v[32:33], v[152:153] op_sel_hi:[1,0]
.Lmx_norescale:
	v_sub_f32_e32 v66, v66, v168
	v_sub_f32_e32 v67, v67, v168
	v_sub_f32_e32 v68, v68, v168
	v_sub_f32_e32 v69, v69, v168
	v_sub_f32_e32 v70, v70, v168
	v_sub_f32_e32 v71, v71, v168
	v_sub_f32_e32 v72, v72, v168
	v_sub_f32_e32 v73, v73, v168
	v_sub_f32_e32 v74, v74, v168
	v_sub_f32_e32 v75, v75, v168
	v_sub_f32_e32 v76, v76, v168
	v_sub_f32_e32 v77, v77, v168
	v_sub_f32_e32 v78, v78, v168
	v_sub_f32_e32 v79, v79, v168
	v_sub_f32_e32 v80, v80, v168
	v_sub_f32_e32 v81, v81, v168
	v_exp_f32_e32 v66, v66
	v_exp_f32_e32 v67, v67
	v_exp_f32_e32 v68, v68
	v_exp_f32_e32 v69, v69
	v_exp_f32_e32 v70, v70
	v_exp_f32_e32 v71, v71
	v_exp_f32_e32 v72, v72
	v_exp_f32_e32 v73, v73
	v_exp_f32_e32 v74, v74
	v_exp_f32_e32 v75, v75
	v_exp_f32_e32 v76, v76
	v_exp_f32_e32 v77, v77
	v_exp_f32_e32 v78, v78
	v_exp_f32_e32 v79, v79
	v_exp_f32_e32 v80, v80
	v_exp_f32_e32 v81, v81
	s_nop 0
	v_add_f32_e32 v146, v66, v67
	v_add_f32_e32 v147, v68, v69
	v_add_f32_e32 v146, v146, v70
	v_add_f32_e32 v147, v147, v71
	v_add_f32_e32 v146, v146, v72
	v_add_f32_e32 v147, v147, v73
	v_add_f32_e32 v146, v146, v74
	v_add_f32_e32 v147, v147, v75
	v_add_f32_e32 v146, v146, v76
	v_add_f32_e32 v147, v147, v77
	v_add_f32_e32 v146, v146, v78
	v_add_f32_e32 v147, v147, v79
	v_add_f32_e32 v146, v146, v80
	v_add_f32_e32 v147, v147, v81
	v_cvt_pk_bf16_f32 v50, v66, v67
	v_cvt_pk_bf16_f32 v51, v68, v69
	v_cvt_pk_bf16_f32 v52, v70, v71
	v_cvt_pk_bf16_f32 v53, v72, v73
	v_cvt_pk_bf16_f32 v54, v74, v75
	v_cvt_pk_bf16_f32 v55, v76, v77
	v_cvt_pk_bf16_f32 v56, v78, v79
	v_cvt_pk_bf16_f32 v57, v80, v81
	v_add_f32_e32 v146, v146, v147
	v_mov_b32_e32 v155, v146
	s_nop 1
	v_permlane32_swap_b32_e32 v146, v155
	v_add_f32_e32 v146, v146, v155
	v_add_f32_e32 v169, v169, v146
	s_waitcnt lgkmcnt(0)
	v_mfma_f32_32x32x16_bf16 v[2:17], v[130:133], v[50:53], v[2:17]
	v_mfma_f32_32x32x16_bf16 v[18:33], v[138:141], v[50:53], v[18:33]
	v_mfma_f32_32x32x16_bf16 v[2:17], v[134:137], v[54:57], v[2:17]
	v_mfma_f32_32x32x16_bf16 v[18:33], v[142:145], v[54:57], v[18:33]
	v_subrev_u32_e32 v65, 32, v65
	s_mov_b32 s47, s43
	s_mov_b32 s43, s44
	s_mov_b32 s44, s45
	s_mov_b32 s45, s47
	s_add_u32 s42, s42, 1
	s_cmp_lt_u32 s42, 8
	s_cbranch_scc1 .Lmx_loop
	s_waitcnt vmcnt(0)
	s_nop 15
	s_nop 7
	v_readlane_b32 s38, v156, 0
	v_readlane_b32 s39, v156, 1
	v_readlane_b32 s40, v156, 2
	v_readlane_b32 s41, v156, 3
	v_readlane_b32 s42, v156, 4
	v_readlane_b32 s43, v156, 5
	v_readlane_b32 s44, v156, 6
	v_readlane_b32 s45, v156, 7
	v_readlane_b32 s46, v156, 8
	v_readlane_b32 s47, v156, 9
	v_readlane_b32 s48, v156, 10
	v_readlane_b32 s49, v156, 11
	s_branch .LBB0_709

.LBB0_711:
	s_cmp_gt_i32 s48, 3
	s_cbranch_scc0 .LBB0_710
	s_mov_b32 s47, -1

.LBB0_720:
	s_cmp_gt_i32 s48, 3
	s_cbranch_scc0 .LBB0_719
	s_mov_b32 s44, -1
